# grid barrier: the two generation-word spin loops poll back to back (s_sleep 1 removed)
# speedup vs baseline: 1.0061x; 1.0032x over previous
.LBB0_828:
	s_and_b32 s9, s6, 0xff
	s_mov_b64 s[38:39], -1
	s_cmp_lg_u32 s9, 0
	s_mov_b64 s[44:45], -1
	s_cbranch_scc1 .LBB0_831
	v_readlane_b32 s10, v252, 35
	v_readlane_b32 s11, v252, 36
	s_nop 4
	global_load_dword v0, v141, s[10:11] sc1
	s_waitcnt vmcnt(0)
	v_cmp_eq_u32_e32 vcc, 0, v0
	s_cbranch_vccnz .LBB0_833
	s_mov_b64 s[44:45], 0
	s_mov_b64 s[42:43], -1
